# plus: last spare-LDS piece moved to the second load batch and both gate-vector load pairs issued together (no global residual load left in the second batch)
# speedup vs baseline: 1.0341x; 1.0033x over previous
.Lxr_g4:
	v_lshl_add_u64 v[98:99], v[0:1], 1, s[10:11]
	global_load_dwordx4 v[98:101], v[98:99], off
	s_cmp_lt_i32 s16, 42
	s_cselect_b32 s0, s0, s1
	s_bitcmp1_b32 s0, 0
	s_cselect_b64 s[4:5], -1, 0
	s_mul_i32 s68, s12, 0x1800
	s_movk_i32 s0, 0x1fff
	s_and_b64 vcc, exec, s[4:5]
	v_mov_b64_e32 v[106:107], s[68:69]
	v_cmp_lt_i32_e64 s[0:1], s0, v249
	s_cbranch_vccnz .LBB0_896
	s_add_i32 s12, s14, 0xffffe000
	s_lshr_b32 s12, s12, 10
	s_mulk_i32 s12, 0x1800
	s_addk_i32 s12, 0x1800
	v_mov_b32_e32 v0, s12
	v_cndmask_b32_e64 v0, 0, v0, s[0:1]
	v_mov_b64_e32 v[106:107], v[0:1]
.LBB0_896:
	v_readlane_b32 s0, v254, 38
	v_readlane_b32 s1, v254, 39
	s_xor_b64 s[18:19], s[4:5], -1
	s_lshl_b64 s[0:1], s[0:1], 2
	s_add_u32 s4, s24, s0
	s_addc_u32 s5, s25, s1
	v_readlane_b32 s0, v254, 47
	v_readlane_b32 s1, v254, 48
	s_and_b64 s[0:1], s[0:1], exec
	s_movk_i32 s0, 0x5000
	s_cselect_b32 s0, 0x2000, s0
	s_add_u32 s12, s4, s0
	s_addc_u32 s13, s5, 0
	v_ashrrev_i32_e32 v243, 31, v242
	v_lshl_add_u64 v[106:107], v[106:107], 2, s[12:13]
	v_lshl_add_u64 v[106:107], v[242:243], 2, v[106:107]
	flat_load_dwordx4 v[210:213], v[106:107] offset:16
	flat_load_dwordx4 v[214:217], v[106:107]
	flat_load_dwordx4 v[206:209], v[106:107] offset:528
	flat_load_dwordx2 v[244:245], v[106:107] offset:512
	flat_load_dwordx2 v[250:251], v[106:107] offset:520
	v_cndmask_b32_e64 v0, 0, 1, s[18:19]
	s_movk_i32 s0, 0x1fef
	v_cmp_lt_i32_e64 s[4:5], s0, v249
	v_cmp_ne_u32_e64 s[0:1], 1, v0
	s_andn2_b64 vcc, exec, s[18:19]
	s_waitcnt vmcnt(0) lgkmcnt(0)
	v_mov_b64_e32 v[186:187], v[210:211]
	v_mov_b64_e32 v[194:195], v[214:215]
	v_mov_b64_e32 v[188:189], v[212:213]
	v_mov_b64_e32 v[196:197], v[216:217]
	s_cbranch_vccnz .LBB0_898
	s_add_i32 s15, s14, 0xffffe010
	s_lshr_b32 s15, s15, 10
	s_mulk_i32 s15, 0x1800
	s_addk_i32 s15, 0x1800
	v_mov_b32_e32 v0, s15
	v_cndmask_b32_e64 v0, 0, v0, s[4:5]
	v_lshl_add_u64 v[106:107], v[0:1], 2, s[12:13]
	v_lshl_add_u64 v[106:107], v[242:243], 2, v[106:107]
	flat_load_dwordx4 v[194:197], v[106:107]
	flat_load_dwordx4 v[186:189], v[106:107] offset:16

.Lxr_d2:
	v_add_u32_e32 v118, 0x4000, v0
	v_mov_b32_e32 v119, v1
	v_add_u32_e32 v0, 0x8000, v0
	v_lshl_add_u64 v[118:119], v[118:119], 1, s[10:11]
	v_lshl_add_u64 v[120:121], v[0:1], 1, s[10:11]
	s_cmp_eq_u32 s98, 0
	s_cbranch_scc1 .Lxl_g_3
	v_mbcnt_lo_u32_b32 v118, -1, 0
	v_mbcnt_hi_u32_b32 v118, -1, v118
	v_readlane_b32 s100, v255, 46
	v_readlane_b32 s101, v255, 47
	v_lshl_add_u32 v118, v118, 4, s99
	s_nop 0
	v_writelane_b32 v142, s100, 63
	v_writelane_b32 v143, s101, 63
	v_readlane_b32 s100, v255, 48
	v_readlane_b32 s101, v255, 49
	s_nop 1
	v_writelane_b32 v144, s100, 63
	v_writelane_b32 v145, s101, 63
	s_bitset0_b64 exec, 63
	ds_read_b128 v[142:145], v118 offset:3072
	s_mov_b64 exec, -1
	s_branch .Lxl_d_3
.Lxl_g_3:
	global_load_dwordx4 v[142:145], v[118:119], off
.Lxl_d_3:
	s_nop 0
	s_cmp_eq_u32 s98, 0
	s_cbranch_scc1 .Lxr_g5
	v_mov_b32_e32 v118, v202
	v_mov_b32_e32 v119, v203
	v_mov_b32_e32 v120, v204
	v_mov_b32_e32 v121, v205
	s_branch .Lxr_d5

.LBB0_908:
	v_lshl_add_u64 v[130:131], v[130:131], 2, s[12:13]
	v_lshl_add_u64 v[130:131], v[242:243], 2, v[130:131]
	v_mov_b64_e32 v[234:235], v[206:207]
	v_mov_b64_e32 v[236:237], v[208:209]
	v_mov_b64_e32 v[238:239], v[244:245]
	v_mov_b64_e32 v[240:241], v[250:251]
	s_and_b64 vcc, exec, s[0:1]
	s_waitcnt vmcnt(0) lgkmcnt(0)
	v_mov_b64_e32 v[222:223], v[234:235]
	v_mov_b64_e32 v[226:227], v[238:239]
	v_mov_b64_e32 v[224:225], v[236:237]
	v_mov_b64_e32 v[228:229], v[240:241]
	s_cbranch_vccnz .LBB0_910
	s_add_i32 s4, s14, 0xffffe010
	s_lshr_b32 s4, s4, 10
	s_mulk_i32 s4, 0x1800
	s_addk_i32 s4, 0x1800
	v_mov_b32_e32 v0, s4
	s_movk_i32 s4, 0x1fef
	v_cmp_lt_i32_e32 vcc, s4, v249
	s_nop 1
	v_cndmask_b32_e32 v0, 0, v0, vcc
	v_lshl_add_u64 v[130:131], v[0:1], 2, s[12:13]
	v_lshl_add_u64 v[130:131], v[242:243], 2, v[130:131]
	flat_load_dwordx4 v[226:229], v[130:131] offset:512
	flat_load_dwordx4 v[222:225], v[130:131] offset:528

.LBB0_1011:
	v_lshlrev_b64 v[2:3], 1, v[0:1]
	v_cvt_pk_bf16_f32 v68, v52, v53
	v_cvt_pk_bf16_f32 v69, v54, v55
	v_cvt_pk_bf16_f32 v70, v56, v57
	v_cvt_pk_bf16_f32 v71, v58, v59
	v_lshl_add_u64 v[72:73], s[10:11], 0, v[2:3]
	v_readlane_b32 s100, v68, 63
	v_readlane_b32 s101, v69, 63
	v_mbcnt_lo_u32_b32 v72, -1, 0
	v_mbcnt_hi_u32_b32 v72, -1, v72
	v_writelane_b32 v255, s100, 46
	v_writelane_b32 v255, s101, 47
	v_readlane_b32 s100, v70, 63
	v_readlane_b32 s101, v71, 63
	v_lshl_add_u32 v72, v72, 4, s99
	s_nop 0
	v_writelane_b32 v255, s100, 48
	v_writelane_b32 v255, s101, 49
	s_bitset0_b64 exec, 63
	ds_write_b128 v72, v[68:71] offset:3072
	s_mov_b64 exec, -1
	v_lshl_add_u64 v[2:3], s[78:79], 0, v[2:3]
	s_nop 0
	v_pk_fma_f32 v[70:71], v[54:55], v[38:39], v[30:31]
	v_pk_fma_f32 v[68:69], v[52:53], v[36:37], v[28:29]
	v_pk_fma_f32 v[72:73], v[58:59], v[46:47], v[22:23]
	v_pk_fma_f32 v[74:75], v[56:57], v[44:45], v[20:21]
	v_cvt_pk_bf16_f32 v68, v68, v69
	v_cvt_pk_bf16_f32 v69, v70, v71
	v_cvt_pk_bf16_f32 v71, v72, v73
	s_nop 0
	v_cvt_pk_bf16_f32 v70, v74, v75
	global_store_dwordx4 v[2:3], v[68:71], off
	s_branch .LBB0_1013
